# barrier relocation + static s_setprio 3 for waves 4-7 inside all four mixer unit types
# baseline (speedup 1.0000x reference)
; #define QLOOP2(qi_, r2_, n_, ...) for (;;) { if (tid == 0) s_item = (int)atomicAdd(ctr + 64 * (qi_) + 32 * (r2_), 1u); __syncthreads(); const int item = s_item; __syncthreads(); if (item >= (n_)) break; __VA_ARGS__ }
; template <int PHM, int MIXM>
; __global__ void __launch_bounds__(512, 2) mega(Args Aval) {
;     ...
;             for (int r2 = 0; r2 < ((PROBE_DUP & 16) ? 2 : 1); ++r2) if (MIXM & 1) QLOOP2(0, r2, 256, { const int L = 15 - (item >> 4), r = item & 15; flash_unit<0>(A, l, r >> 2, r & 3, L, lds); })
.LBB0_735:
	s_or_b64 exec, exec, s[2:3]
	s_waitcnt vmcnt(0) lgkmcnt(0)
	s_barrier
	ds_read_b32 v0, v177 offset:8
	s_mov_b64 s[2:3], -1
	s_waitcnt lgkmcnt(0)
	s_barrier
	v_cmp_gt_i32_e32 vcc, s68, v0
	v_readfirstlane_b32 s4, v0
	s_cbranch_vccz .LBB0_730
	v_readfirstlane_b32 s100, v238
	s_cmp_lt_u32 s100, 0x100
	s_cbranch_scc1 .Lprio_skip_mla
	s_setprio 3

; #define QLOOP2(qi_, r2_, n_, ...) for (;;) { if (tid == 0) s_item = (int)atomicAdd(ctr + 64 * (qi_) + 32 * (r2_), 1u); __syncthreads(); const int item = s_item; __syncthreads(); if (item >= (n_)) break; __VA_ARGS__ }
; template <int PHM, int MIXM>
; __global__ void __launch_bounds__(512, 2) mega(Args Aval) {
;     ...
;             for (int r2 = 0; r2 < ((PROBE_DUP & 16) ? 2 : 1); ++r2) if (MIXM & 1) QLOOP2(0, r2, 256, { const int L = 15 - (item >> 4), r = item & 15; flash_unit<0>(A, l, r >> 2, r & 3, L, lds); })
;             for (int r2 = 0; r2 < ((PROBE_DUP & 32) ? 2 : 1); ++r2) if (MIXM & 2) QLOOP2(1, r2, 256, { const int L = 15 - (item >> 4), r = item & 15; flash_unit<2>(A, l, r >> 2, r & 3, L, lds); })
.LBB0_765:
	s_or_b64 exec, exec, s[2:3]
	s_waitcnt lgkmcnt(0)
	s_barrier
	ds_read_b32 v0, v177 offset:8
	s_mov_b64 s[2:3], -1
	s_waitcnt lgkmcnt(0)
	s_barrier
	v_cmp_gt_i32_e32 vcc, s68, v0
	v_readfirstlane_b32 s5, v0
	s_cbranch_vccz .LBB0_760
	v_readfirstlane_b32 s100, v238
	s_cmp_lt_u32 s100, 0x100
	s_cbranch_scc1 .Lprio_skip_ret
	s_setprio 3

; #define QLOOP2(qi_, r2_, n_, ...) for (;;) { if (tid == 0) s_item = (int)atomicAdd(ctr + 64 * (qi_) + 32 * (r2_), 1u); __syncthreads(); const int item = s_item; __syncthreads(); if (item >= (n_)) break; __VA_ARGS__ }
; template <int PHM, int MIXM>
; __global__ void __launch_bounds__(512, 2) mega(Args Aval) {
;     ...
;             for (int r2 = 0; r2 < ((PROBE_DUP & 16) ? 2 : 1); ++r2) if (MIXM & 1) QLOOP2(0, r2, 256, { const int L = 15 - (item >> 4), r = item & 15; flash_unit<0>(A, l, r >> 2, r & 3, L, lds); })
;             for (int r2 = 0; r2 < ((PROBE_DUP & 32) ? 2 : 1); ++r2) if (MIXM & 2) QLOOP2(1, r2, 256, { const int L = 15 - (item >> 4), r = item & 15; flash_unit<2>(A, l, r >> 2, r & 3, L, lds); })
;             for (int r2 = 0; r2 < ((PROBE_DUP & 64) ? 2 : 1); ++r2) if (MIXM & 8) QLOOP2(2, r2, 256, { s5_unit(A, l, item, lds, wave, lane); })
.LBB0_790:
	s_or_b64 exec, exec, s[2:3]
	s_waitcnt lgkmcnt(0)
	s_barrier
	ds_read_b32 v0, v177 offset:8
	s_mov_b64 s[2:3], -1
	s_waitcnt lgkmcnt(0)
	s_barrier
	v_cmp_gt_i32_e32 vcc, s68, v0
	v_readfirstlane_b32 s4, v0
	s_cbranch_vccz .LBB0_785
	v_readfirstlane_b32 s100, v238
	s_cmp_lt_u32 s100, 0x100
	s_cbranch_scc1 .Lprio_skip_s5
	s_setprio 3

; #define QLOOP2(qi_, r2_, n_, ...) for (;;) { if (tid == 0) s_item = (int)atomicAdd(ctr + 64 * (qi_) + 32 * (r2_), 1u); __syncthreads(); const int item = s_item; __syncthreads(); if (item >= (n_)) break; __VA_ARGS__ }
; template <int PHM, int MIXM>
; __global__ void __launch_bounds__(512, 2) mega(Args Aval) {
;     ...
;             for (int r2 = 0; r2 < ((PROBE_DUP & 16) ? 2 : 1); ++r2) if (MIXM & 1) QLOOP2(0, r2, 256, { const int L = 15 - (item >> 4), r = item & 15; flash_unit<0>(A, l, r >> 2, r & 3, L, lds); })
;             for (int r2 = 0; r2 < ((PROBE_DUP & 32) ? 2 : 1); ++r2) if (MIXM & 2) QLOOP2(1, r2, 256, { const int L = 15 - (item >> 4), r = item & 15; flash_unit<2>(A, l, r >> 2, r & 3, L, lds); })
;             for (int r2 = 0; r2 < ((PROBE_DUP & 64) ? 2 : 1); ++r2) if (MIXM & 8) QLOOP2(2, r2, 256, { s5_unit(A, l, item, lds, wave, lane); })
;             for (int r2 = 0; r2 < ((PROBE_DUP & 128) ? 2 : 1); ++r2) if (MIXM & 4) QLOOP2(3, r2, 512, { const int L = 31 - (item >> 4), r = item & 15; flash_unit<1>(A, l, r >> 2, r & 3, L, lds); })
.LBB0_801:
	s_or_b64 exec, exec, s[2:3]
	s_waitcnt lgkmcnt(0)
	s_barrier
	ds_read_b32 v0, v177 offset:8
	s_movk_i32 s2, 0x1ff
	s_waitcnt lgkmcnt(0)
	s_barrier
	v_cmp_lt_i32_e32 vcc, s2, v0
	v_readfirstlane_b32 s4, v0
	s_mov_b64 s[2:3], -1
	s_cbranch_vccnz .LBB0_796
	v_readfirstlane_b32 s100, v238
	s_cmp_lt_u32 s100, 0x100
	s_cbranch_scc1 .Lprio_skip_diff
	s_setprio 3
